# GEMM K-loop heads aligned to 64 bytes (.p2align 6)
# baseline (speedup 1.0000x reference)
; template <class Epi, class Sched, bool ALIGN_EPI = false, bool SP2 = false>
; __device__ __forceinline__ void gemm_phase(PG8_LAS unsigned char* lds, const Gemm g, const Sched& S, const Epi& E) {
;     ...
;         const char* nA = has_next ? (const char*)(nxt.part ? g.A1 : g.A) + (size_t)nxt.pm * tstep : cA; const char* nB = has_next ? (const char*)(nxt.part ? g.Bt1 : g.Bt) + (size_t)nxt.pn * tstep : cB;
;         for (int t = 0; t < nt; t += 2) {
;             const bool last = (t == nt - 2);
;             const char* a1 = cA + (size_t)(t + 1) * kstep;
;             const char* a2 = last ? nA : cA + (size_t)(t + 2) * kstep; const char* b2 = last ? nB : cB + (size_t)(t + 2) * kstep;
;     ...
;         for (int a = 0; a < 2; ++a)
; #pragma unroll
;             for (int b = 0; b < 2; ++b)
; #pragma unroll
;                 for (int m = 0; m < 4; ++m)
; #pragma unroll
;                     for (int n = 0; n < 2; ++n) acc[a][b][m][n] = (f32x4){0.f, 0.f, 0.f, 0.f};
;         }
;         cur = nxt; cA = nA; cB = nB; ++ui;
.LBB0_164:
	s_ashr_i32 s25, s24, 31
	s_lshl_b64 s[36:37], s[24:25], 20
	s_add_u32 s36, s56, s36
	s_addc_u32 s37, s57, s37
	s_and_b64 s[40:41], s[38:39], exec
	s_cselect_b32 s17, s37, s27
	s_cselect_b32 s25, s36, s26
	s_ashr_i32 s23, s22, 31
	s_lshl_b64 s[40:41], s[22:23], 20
	s_add_u32 s42, s47, s40
	s_addc_u32 s43, s48, s41
	s_and_b64 s[40:41], s[38:39], exec
	s_cselect_b32 s23, s43, s29
	s_cselect_b32 s54, s42, s28
	s_add_u32 s26, s26, 0x80080
	s_addc_u32 s27, s27, 0
	s_add_u32 s55, s28, 0x100
	v_mov_b32_e32 v2, 0
	s_addc_u32 s73, s29, 0
	s_mov_b32 s77, -2
	v_mov_b32_e32 v3, v2
	v_mov_b32_e32 v4, v2
	v_mov_b32_e32 v5, v2
	v_mov_b32_e32 v10, v2
	v_mov_b32_e32 v11, v2
	v_mov_b32_e32 v12, v2
	v_mov_b32_e32 v13, v2
	s_waitcnt lgkmcnt(0)
	v_mov_b32_e32 v18, v2
	v_mov_b32_e32 v19, v2
	v_mov_b32_e32 v20, v2
	v_mov_b32_e32 v21, v2
	v_mov_b32_e32 v26, v2
	v_mov_b32_e32 v27, v2
	v_mov_b32_e32 v28, v2
	v_mov_b32_e32 v29, v2
	v_mov_b32_e32 v34, v2
	v_mov_b32_e32 v35, v2
	v_mov_b32_e32 v36, v2
	v_mov_b32_e32 v37, v2
	v_mov_b32_e32 v42, v2
	v_mov_b32_e32 v43, v2
	v_mov_b32_e32 v44, v2
	v_mov_b32_e32 v45, v2
	v_mov_b32_e32 v50, v2
	v_mov_b32_e32 v51, v2
	v_mov_b32_e32 v52, v2
	v_mov_b32_e32 v53, v2
	v_mov_b32_e32 v58, v2
	v_mov_b32_e32 v59, v2
	v_mov_b32_e32 v60, v2
	v_mov_b32_e32 v61, v2
	v_mov_b32_e32 v6, v2
	v_mov_b32_e32 v7, v2
	v_mov_b32_e32 v8, v2
	v_mov_b32_e32 v9, v2
	v_mov_b32_e32 v14, v2
	v_mov_b32_e32 v15, v2
	v_mov_b32_e32 v16, v2
	v_mov_b32_e32 v17, v2
	v_mov_b32_e32 v22, v2
	v_mov_b32_e32 v23, v2
	v_mov_b32_e32 v24, v2
	v_mov_b32_e32 v25, v2
	v_mov_b32_e32 v30, v2
	v_mov_b32_e32 v31, v2
	v_mov_b32_e32 v32, v2
	v_mov_b32_e32 v33, v2
	v_mov_b32_e32 v38, v2
	v_mov_b32_e32 v39, v2
	v_mov_b32_e32 v40, v2
	v_mov_b32_e32 v41, v2
	v_mov_b32_e32 v46, v2
	v_mov_b32_e32 v47, v2
	v_mov_b32_e32 v48, v2
	v_mov_b32_e32 v49, v2
	v_mov_b32_e32 v54, v2
	v_mov_b32_e32 v55, v2
	v_mov_b32_e32 v56, v2
	v_mov_b32_e32 v57, v2
	v_mov_b32_e32 v62, v2
	v_mov_b32_e32 v63, v2
	v_mov_b32_e32 v64, v2
	v_mov_b32_e32 v65, v2
	v_mov_b32_e32 v66, v2
	v_mov_b32_e32 v67, v2
	v_mov_b32_e32 v68, v2
	v_mov_b32_e32 v69, v2
	v_mov_b32_e32 v74, v2
	v_mov_b32_e32 v75, v2
	v_mov_b32_e32 v76, v2
	v_mov_b32_e32 v77, v2
	v_mov_b32_e32 v82, v2
	v_mov_b32_e32 v83, v2
	v_mov_b32_e32 v84, v2
	v_mov_b32_e32 v85, v2
	v_mov_b32_e32 v90, v2
	v_mov_b32_e32 v91, v2
	v_mov_b32_e32 v92, v2
	v_mov_b32_e32 v93, v2
	v_mov_b32_e32 v98, v2
	v_mov_b32_e32 v99, v2
	v_mov_b32_e32 v100, v2
	v_mov_b32_e32 v101, v2
	v_mov_b32_e32 v106, v2
	v_mov_b32_e32 v107, v2
	v_mov_b32_e32 v108, v2
	v_mov_b32_e32 v109, v2
	v_mov_b32_e32 v114, v2
	v_mov_b32_e32 v115, v2
	v_mov_b32_e32 v116, v2
	v_mov_b32_e32 v117, v2
	v_mov_b32_e32 v122, v2
	v_mov_b32_e32 v123, v2
	v_mov_b32_e32 v124, v2
	v_mov_b32_e32 v125, v2
	v_mov_b32_e32 v70, v2
	v_mov_b32_e32 v71, v2
	v_mov_b32_e32 v72, v2
	v_mov_b32_e32 v73, v2
	v_mov_b32_e32 v78, v2
	v_mov_b32_e32 v79, v2
	v_mov_b32_e32 v80, v2
	v_mov_b32_e32 v81, v2
	v_mov_b32_e32 v86, v2
	v_mov_b32_e32 v87, v2
	v_mov_b32_e32 v88, v2
	v_mov_b32_e32 v89, v2
	v_mov_b32_e32 v94, v2
	v_mov_b32_e32 v95, v2
	v_mov_b32_e32 v96, v2
	v_mov_b32_e32 v97, v2
	v_mov_b32_e32 v102, v2
	v_mov_b32_e32 v103, v2
	v_mov_b32_e32 v104, v2
	v_mov_b32_e32 v105, v2
	v_mov_b32_e32 v110, v2
	v_mov_b32_e32 v111, v2
	v_mov_b32_e32 v112, v2
	v_mov_b32_e32 v113, v2
	v_mov_b32_e32 v118, v2
	v_mov_b32_e32 v119, v2
	v_mov_b32_e32 v120, v2
	v_mov_b32_e32 v121, v2
	v_mov_b32_e32 v126, v2
	v_mov_b32_e32 v127, v2
	v_mov_b32_e32 v128, v2
	v_mov_b32_e32 v129, v2
	.p2align 6

; template <class Epi, class Sched, bool ALIGN_EPI = false, bool SP2 = false>
; __device__ __forceinline__ void gemm_phase(PG8_LAS unsigned char* lds, const Gemm g, const Sched& S, const Epi& E) {
;     ...
;         const char* nA = has_next ? (const char*)(nxt.part ? g.A1 : g.A) + (size_t)nxt.pm * tstep : cA; const char* nB = has_next ? (const char*)(nxt.part ? g.Bt1 : g.Bt) + (size_t)nxt.pn * tstep : cB;
;         for (int t = 0; t < nt; t += 2) {
;             const bool last = (t == nt - 2);
;             const char* a1 = cA + (size_t)(t + 1) * kstep;
;             const char* a2 = last ? nA : cA + (size_t)(t + 2) * kstep; const char* b2 = last ? nB : cB + (size_t)(t + 2) * kstep;
.LBB0_428:
	s_ashr_i32 s21, s20, 31
	s_and_b32 s50, s49, 1
	s_lshl_b64 s[22:23], s[20:21], 19
	s_cmp_eq_u32 s50, 0
	s_cselect_b32 s21, s60, s12
	s_cselect_b32 s19, s61, s13
	s_cselect_b32 s28, s4, s45
	s_cselect_b32 s29, s36, s46
	s_add_u32 s22, s21, s22
	s_addc_u32 s23, s19, s23
	s_and_b64 s[24:25], s[40:41], exec
	s_cselect_b32 s21, s23, s17
	s_cselect_b32 s52, s22, s16
	s_ashr_i32 s19, s18, 31
	s_lshl_b64 s[24:25], s[18:19], 19
	s_add_u32 s24, s28, s24
	s_addc_u32 s25, s29, s25
	s_and_b64 s[28:29], s[40:41], exec
	s_cselect_b32 s19, s25, s27
	s_cselect_b32 s53, s24, s26
	s_add_u32 s16, s16, 0x40080
	s_addc_u32 s17, s17, 0
	s_add_u32 s73, s26, 0x100
	s_addc_u32 s77, s27, 0
	s_mov_b32 s78, -2
	.p2align 6

; template <class Epi, class Sched, bool ALIGN_EPI = false, bool SP2 = false>
; __device__ __forceinline__ void gemm_phase(PG8_LAS unsigned char* lds, const Gemm g, const Sched& S, const Epi& E) {
;     ...
;         const char* nA = has_next ? (const char*)(nxt.part ? g.A1 : g.A) + (size_t)nxt.pm * tstep : cA; const char* nB = has_next ? (const char*)(nxt.part ? g.Bt1 : g.Bt) + (size_t)nxt.pn * tstep : cB;
;         for (int t = 0; t < nt; t += 2) {
;             const bool last = (t == nt - 2);
;             const char* a1 = cA + (size_t)(t + 1) * kstep;
;             const char* a2 = last ? nA : cA + (size_t)(t + 2) * kstep; const char* b2 = last ? nB : cB + (size_t)(t + 2) * kstep;
;     ...
;         for (int a = 0; a < 2; ++a)
; #pragma unroll
;             for (int b = 0; b < 2; ++b)
; #pragma unroll
;                 for (int m = 0; m < 4; ++m)
; #pragma unroll
;                     for (int n = 0; n < 2; ++n) acc[a][b][m][n] = (f32x4){0.f, 0.f, 0.f, 0.f};
;         }
;         cur = nxt; cA = nA; cB = nB; ++ui;
.LBB0_552:
	s_ashr_i32 s23, s22, 31
	s_lshl_b64 s[24:25], s[22:23], 20
	s_add_u32 s24, s14, s24
	s_addc_u32 s25, s15, s25
	s_and_b64 s[28:29], s[44:45], exec
	s_cselect_b32 s23, s25, s17
	s_cselect_b32 s38, s24, s16
	s_ashr_i32 s21, s20, 31
	s_lshl_b64 s[28:29], s[20:21], 20
	s_add_u32 s36, s46, s28
	s_addc_u32 s37, s47, s29
	s_and_b64 s[28:29], s[44:45], exec
	s_cselect_b32 s21, s37, s27
	s_cselect_b32 s39, s36, s26
	s_add_u32 s16, s16, 0x80080
	s_addc_u32 s17, s17, 0
	s_add_u32 s78, s26, 0x100
	v_mov_b32_e32 v2, 0
	s_addc_u32 vcc_lo, s27, 0
	s_mov_b32 vcc_hi, -2
	s_waitcnt lgkmcnt(0)
	v_mov_b32_e32 v3, v2
	v_mov_b32_e32 v4, v2
	v_mov_b32_e32 v5, v2
	v_mov_b32_e32 v6, v2
	v_mov_b32_e32 v7, v2
	v_mov_b32_e32 v8, v2
	v_mov_b32_e32 v9, v2
	v_mov_b32_e32 v18, v2
	v_mov_b32_e32 v19, v2
	v_mov_b32_e32 v20, v2
	v_mov_b32_e32 v21, v2
	v_mov_b32_e32 v22, v2
	v_mov_b32_e32 v23, v2
	v_mov_b32_e32 v24, v2
	v_mov_b32_e32 v25, v2
	v_mov_b32_e32 v34, v2
	v_mov_b32_e32 v35, v2
	v_mov_b32_e32 v36, v2
	v_mov_b32_e32 v37, v2
	v_mov_b32_e32 v38, v2
	v_mov_b32_e32 v39, v2
	v_mov_b32_e32 v40, v2
	v_mov_b32_e32 v41, v2
	v_mov_b32_e32 v50, v2
	v_mov_b32_e32 v51, v2
	v_mov_b32_e32 v52, v2
	v_mov_b32_e32 v53, v2
	v_mov_b32_e32 v54, v2
	v_mov_b32_e32 v55, v2
	v_mov_b32_e32 v56, v2
	v_mov_b32_e32 v57, v2
	v_mov_b32_e32 v10, v2
	v_mov_b32_e32 v11, v2
	v_mov_b32_e32 v12, v2
	v_mov_b32_e32 v13, v2
	v_mov_b32_e32 v14, v2
	v_mov_b32_e32 v15, v2
	v_mov_b32_e32 v16, v2
	v_mov_b32_e32 v17, v2
	v_mov_b32_e32 v26, v2
	v_mov_b32_e32 v27, v2
	v_mov_b32_e32 v28, v2
	v_mov_b32_e32 v29, v2
	v_mov_b32_e32 v30, v2
	v_mov_b32_e32 v31, v2
	v_mov_b32_e32 v32, v2
	v_mov_b32_e32 v33, v2
	v_mov_b32_e32 v42, v2
	v_mov_b32_e32 v43, v2
	v_mov_b32_e32 v44, v2
	v_mov_b32_e32 v45, v2
	v_mov_b32_e32 v46, v2
	v_mov_b32_e32 v47, v2
	v_mov_b32_e32 v48, v2
	v_mov_b32_e32 v49, v2
	v_mov_b32_e32 v58, v2
	v_mov_b32_e32 v59, v2
	v_mov_b32_e32 v60, v2
	v_mov_b32_e32 v61, v2
	v_mov_b32_e32 v62, v2
	v_mov_b32_e32 v63, v2
	v_mov_b32_e32 v64, v2
	v_mov_b32_e32 v65, v2
	v_mov_b32_e32 v66, v2
	v_mov_b32_e32 v67, v2
	v_mov_b32_e32 v68, v2
	v_mov_b32_e32 v69, v2
	v_mov_b32_e32 v70, v2
	v_mov_b32_e32 v71, v2
	v_mov_b32_e32 v72, v2
	v_mov_b32_e32 v73, v2
	v_mov_b32_e32 v82, v2
	v_mov_b32_e32 v83, v2
	v_mov_b32_e32 v84, v2
	v_mov_b32_e32 v85, v2
	v_mov_b32_e32 v86, v2
	v_mov_b32_e32 v87, v2
	v_mov_b32_e32 v88, v2
	v_mov_b32_e32 v89, v2
	v_mov_b32_e32 v98, v2
	v_mov_b32_e32 v99, v2
	v_mov_b32_e32 v100, v2
	v_mov_b32_e32 v101, v2
	v_mov_b32_e32 v102, v2
	v_mov_b32_e32 v103, v2
	v_mov_b32_e32 v104, v2
	v_mov_b32_e32 v105, v2
	v_mov_b32_e32 v126, v2
	v_mov_b32_e32 v127, v2
	v_mov_b32_e32 v128, v2
	v_mov_b32_e32 v129, v2
	v_mov_b32_e32 v130, v2
	v_mov_b32_e32 v131, v2
	v_mov_b32_e32 v132, v2
	v_mov_b32_e32 v133, v2
	v_mov_b32_e32 v74, v2
	v_mov_b32_e32 v75, v2
	v_mov_b32_e32 v76, v2
	v_mov_b32_e32 v77, v2
	v_mov_b32_e32 v78, v2
	v_mov_b32_e32 v79, v2
	v_mov_b32_e32 v80, v2
	v_mov_b32_e32 v81, v2
	v_mov_b32_e32 v90, v2
	v_mov_b32_e32 v91, v2
	v_mov_b32_e32 v92, v2
	v_mov_b32_e32 v93, v2
	v_mov_b32_e32 v94, v2
	v_mov_b32_e32 v95, v2
	v_mov_b32_e32 v96, v2
	v_mov_b32_e32 v97, v2
	v_mov_b32_e32 v106, v2
	v_mov_b32_e32 v107, v2
	v_mov_b32_e32 v108, v2
	v_mov_b32_e32 v109, v2
	v_mov_b32_e32 v110, v2
	v_mov_b32_e32 v111, v2
	v_mov_b32_e32 v112, v2
	v_mov_b32_e32 v113, v2
	v_mov_b32_e32 v138, v2
	v_mov_b32_e32 v139, v2
	v_mov_b32_e32 v140, v2
	v_mov_b32_e32 v141, v2
	v_mov_b32_e32 v142, v2
	v_mov_b32_e32 v143, v2
	v_mov_b32_e32 v144, v2
	v_mov_b32_e32 v145, v2
	.p2align 6

; template <class Epi, class Sched, bool ALIGN_EPI = false, bool SP2 = false>
; __device__ __forceinline__ void gemm_phase(PG8_LAS unsigned char* lds, const Gemm g, const Sched& S, const Epi& E) {
;     ...
;         const char* nA = has_next ? (const char*)(nxt.part ? g.A1 : g.A) + (size_t)nxt.pm * tstep : cA; const char* nB = has_next ? (const char*)(nxt.part ? g.Bt1 : g.Bt) + (size_t)nxt.pn * tstep : cB;
;         for (int t = 0; t < nt; t += 2) {
;             const bool last = (t == nt - 2);
;             const char* a1 = cA + (size_t)(t + 1) * kstep;
;             const char* a2 = last ? nA : cA + (size_t)(t + 2) * kstep; const char* b2 = last ? nB : cB + (size_t)(t + 2) * kstep;
;     ...
;         for (int a = 0; a < 2; ++a)
; #pragma unroll
;             for (int b = 0; b < 2; ++b)
; #pragma unroll
;                 for (int m = 0; m < 4; ++m)
; #pragma unroll
;                     for (int n = 0; n < 2; ++n) acc[a][b][m][n] = (f32x4){0.f, 0.f, 0.f, 0.f};
;         }
;         cur = nxt; cA = nA; cB = nB; ++ui;
.LBB0_658:
	s_ashr_i32 s23, s22, 31
	s_lshl_b64 s[24:25], s[22:23], 20
	s_add_u32 s24, s56, s24
	s_addc_u32 s25, s57, s25
	s_and_b64 s[28:29], s[40:41], exec
	s_cselect_b32 s23, s25, s17
	s_cselect_b32 s43, s24, s16
	s_ashr_i32 s21, s20, 31
	s_lshl_b64 s[28:29], s[20:21], 20
	s_add_u32 s36, s39, s28
	s_addc_u32 s37, s44, s29
	s_and_b64 s[28:29], s[40:41], exec
	s_cselect_b32 s21, s37, s27
	s_cselect_b32 s52, s36, s26
	s_add_u32 s16, s16, 0x80080
	s_addc_u32 s17, s17, 0
	s_add_u32 s53, s26, 0x100
	v_mov_b32_e32 v2, 0
	s_addc_u32 s73, s27, 0
	s_mov_b32 s77, -2
	v_mov_b32_e32 v3, v2
	v_mov_b32_e32 v4, v2
	v_mov_b32_e32 v5, v2
	v_mov_b32_e32 v10, v2
	v_mov_b32_e32 v11, v2
	v_mov_b32_e32 v12, v2
	v_mov_b32_e32 v13, v2
	v_mov_b32_e32 v18, v2
	v_mov_b32_e32 v19, v2
	v_mov_b32_e32 v20, v2
	v_mov_b32_e32 v21, v2
	v_mov_b32_e32 v26, v2
	v_mov_b32_e32 v27, v2
	v_mov_b32_e32 v28, v2
	v_mov_b32_e32 v29, v2
	v_mov_b32_e32 v34, v2
	v_mov_b32_e32 v35, v2
	v_mov_b32_e32 v36, v2
	v_mov_b32_e32 v37, v2
	v_mov_b32_e32 v42, v2
	v_mov_b32_e32 v43, v2
	v_mov_b32_e32 v44, v2
	v_mov_b32_e32 v45, v2
	v_mov_b32_e32 v50, v2
	v_mov_b32_e32 v51, v2
	v_mov_b32_e32 v52, v2
	v_mov_b32_e32 v53, v2
	v_mov_b32_e32 v58, v2
	v_mov_b32_e32 v59, v2
	v_mov_b32_e32 v60, v2
	v_mov_b32_e32 v61, v2
	v_mov_b32_e32 v6, v2
	v_mov_b32_e32 v7, v2
	v_mov_b32_e32 v8, v2
	v_mov_b32_e32 v9, v2
	v_mov_b32_e32 v14, v2
	v_mov_b32_e32 v15, v2
	v_mov_b32_e32 v16, v2
	v_mov_b32_e32 v17, v2
	v_mov_b32_e32 v22, v2
	v_mov_b32_e32 v23, v2
	v_mov_b32_e32 v24, v2
	v_mov_b32_e32 v25, v2
	v_mov_b32_e32 v30, v2
	v_mov_b32_e32 v31, v2
	v_mov_b32_e32 v32, v2
	v_mov_b32_e32 v33, v2
	v_mov_b32_e32 v38, v2
	v_mov_b32_e32 v39, v2
	v_mov_b32_e32 v40, v2
	v_mov_b32_e32 v41, v2
	v_mov_b32_e32 v46, v2
	v_mov_b32_e32 v47, v2
	v_mov_b32_e32 v48, v2
	v_mov_b32_e32 v49, v2
	v_mov_b32_e32 v54, v2
	v_mov_b32_e32 v55, v2
	v_mov_b32_e32 v56, v2
	v_mov_b32_e32 v57, v2
	v_mov_b32_e32 v62, v2
	v_mov_b32_e32 v63, v2
	v_mov_b32_e32 v64, v2
	v_mov_b32_e32 v65, v2
	v_mov_b32_e32 v66, v2
	v_mov_b32_e32 v67, v2
	v_mov_b32_e32 v68, v2
	v_mov_b32_e32 v69, v2
	v_mov_b32_e32 v74, v2
	v_mov_b32_e32 v75, v2
	v_mov_b32_e32 v76, v2
	v_mov_b32_e32 v77, v2
	v_mov_b32_e32 v82, v2
	v_mov_b32_e32 v83, v2
	v_mov_b32_e32 v84, v2
	v_mov_b32_e32 v85, v2
	v_mov_b32_e32 v90, v2
	v_mov_b32_e32 v91, v2
	v_mov_b32_e32 v92, v2
	v_mov_b32_e32 v93, v2
	v_mov_b32_e32 v98, v2
	v_mov_b32_e32 v99, v2
	v_mov_b32_e32 v100, v2
	v_mov_b32_e32 v101, v2
	v_mov_b32_e32 v106, v2
	v_mov_b32_e32 v107, v2
	v_mov_b32_e32 v108, v2
	v_mov_b32_e32 v109, v2
	v_mov_b32_e32 v114, v2
	v_mov_b32_e32 v115, v2
	v_mov_b32_e32 v116, v2
	v_mov_b32_e32 v117, v2
	v_mov_b32_e32 v122, v2
	v_mov_b32_e32 v123, v2
	v_mov_b32_e32 v124, v2
	v_mov_b32_e32 v125, v2
	v_mov_b32_e32 v70, v2
	v_mov_b32_e32 v71, v2
	v_mov_b32_e32 v72, v2
	v_mov_b32_e32 v73, v2
	v_mov_b32_e32 v78, v2
	v_mov_b32_e32 v79, v2
	v_mov_b32_e32 v80, v2
	v_mov_b32_e32 v81, v2
	v_mov_b32_e32 v86, v2
	v_mov_b32_e32 v87, v2
	v_mov_b32_e32 v88, v2
	v_mov_b32_e32 v89, v2
	v_mov_b32_e32 v94, v2
	v_mov_b32_e32 v95, v2
	v_mov_b32_e32 v96, v2
	v_mov_b32_e32 v97, v2
	v_mov_b32_e32 v102, v2
	v_mov_b32_e32 v103, v2
	v_mov_b32_e32 v104, v2
	v_mov_b32_e32 v105, v2
	v_mov_b32_e32 v110, v2
	v_mov_b32_e32 v111, v2
	v_mov_b32_e32 v112, v2
	v_mov_b32_e32 v113, v2
	v_mov_b32_e32 v118, v2
	v_mov_b32_e32 v119, v2
	v_mov_b32_e32 v120, v2
	v_mov_b32_e32 v121, v2
	v_mov_b32_e32 v126, v2
	v_mov_b32_e32 v127, v2
	v_mov_b32_e32 v128, v2
	v_mov_b32_e32 v129, v2
	.p2align 6

; template <class Epi, class Sched, bool ALIGN_EPI = false, bool SP2 = false>
; __device__ __forceinline__ void gemm_phase(PG8_LAS unsigned char* lds, const Gemm g, const Sched& S, const Epi& E) {
;     ...
;         for (int a = 0; a < 2; ++a)
; #pragma unroll
;             for (int b = 0; b < 2; ++b)
; #pragma unroll
;                 for (int m = 0; m < 4; ++m)
; #pragma unroll
;                     for (int n = 0; n < 2; ++n) acc[a][b][m][n] = (f32x4){0.f, 0.f, 0.f, 0.f};
;         }
;         cur = nxt; cA = nA; cB = nB; ++ui;
.LBB0_801:
	s_add_u32 s44, s24, 0x100
	v_mov_b32_e32 v2, 0
	s_addc_u32 s45, s25, 0
	s_mov_b32 s78, -2
	s_waitcnt lgkmcnt(0)
	v_mov_b32_e32 v3, v2
	v_mov_b32_e32 v4, v2
	v_mov_b32_e32 v5, v2
	v_mov_b32_e32 v6, v2
	v_mov_b32_e32 v7, v2
	v_mov_b32_e32 v8, v2
	v_mov_b32_e32 v9, v2
	v_mov_b32_e32 v18, v2
	v_mov_b32_e32 v19, v2
	v_mov_b32_e32 v20, v2
	v_mov_b32_e32 v21, v2
	v_mov_b32_e32 v22, v2
	v_mov_b32_e32 v23, v2
	v_mov_b32_e32 v24, v2
	v_mov_b32_e32 v25, v2
	v_mov_b32_e32 v34, v2
	v_mov_b32_e32 v35, v2
	v_mov_b32_e32 v36, v2
	v_mov_b32_e32 v37, v2
	v_mov_b32_e32 v38, v2
	v_mov_b32_e32 v39, v2
	v_mov_b32_e32 v40, v2
	v_mov_b32_e32 v41, v2
	v_mov_b32_e32 v50, v2
	v_mov_b32_e32 v51, v2
	v_mov_b32_e32 v52, v2
	v_mov_b32_e32 v53, v2
	v_mov_b32_e32 v54, v2
	v_mov_b32_e32 v55, v2
	v_mov_b32_e32 v56, v2
	v_mov_b32_e32 v57, v2
	v_mov_b32_e32 v10, v2
	v_mov_b32_e32 v11, v2
	v_mov_b32_e32 v12, v2
	v_mov_b32_e32 v13, v2
	v_mov_b32_e32 v14, v2
	v_mov_b32_e32 v15, v2
	v_mov_b32_e32 v16, v2
	v_mov_b32_e32 v17, v2
	v_mov_b32_e32 v26, v2
	v_mov_b32_e32 v27, v2
	v_mov_b32_e32 v28, v2
	v_mov_b32_e32 v29, v2
	v_mov_b32_e32 v30, v2
	v_mov_b32_e32 v31, v2
	v_mov_b32_e32 v32, v2
	v_mov_b32_e32 v33, v2
	v_mov_b32_e32 v42, v2
	v_mov_b32_e32 v43, v2
	v_mov_b32_e32 v44, v2
	v_mov_b32_e32 v45, v2
	v_mov_b32_e32 v46, v2
	v_mov_b32_e32 v47, v2
	v_mov_b32_e32 v48, v2
	v_mov_b32_e32 v49, v2
	v_mov_b32_e32 v58, v2
	v_mov_b32_e32 v59, v2
	v_mov_b32_e32 v60, v2
	v_mov_b32_e32 v61, v2
	v_mov_b32_e32 v62, v2
	v_mov_b32_e32 v63, v2
	v_mov_b32_e32 v64, v2
	v_mov_b32_e32 v65, v2
	v_mov_b32_e32 v66, v2
	v_mov_b32_e32 v67, v2
	v_mov_b32_e32 v68, v2
	v_mov_b32_e32 v69, v2
	v_mov_b32_e32 v70, v2
	v_mov_b32_e32 v71, v2
	v_mov_b32_e32 v72, v2
	v_mov_b32_e32 v73, v2
	v_mov_b32_e32 v82, v2
	v_mov_b32_e32 v83, v2
	v_mov_b32_e32 v84, v2
	v_mov_b32_e32 v85, v2
	v_mov_b32_e32 v86, v2
	v_mov_b32_e32 v87, v2
	v_mov_b32_e32 v88, v2
	v_mov_b32_e32 v89, v2
	v_mov_b32_e32 v98, v2
	v_mov_b32_e32 v99, v2
	v_mov_b32_e32 v100, v2
	v_mov_b32_e32 v101, v2
	v_mov_b32_e32 v102, v2
	v_mov_b32_e32 v103, v2
	v_mov_b32_e32 v104, v2
	v_mov_b32_e32 v105, v2
	v_mov_b32_e32 v114, v2
	v_mov_b32_e32 v115, v2
	v_mov_b32_e32 v116, v2
	v_mov_b32_e32 v117, v2
	v_mov_b32_e32 v118, v2
	v_mov_b32_e32 v119, v2
	v_mov_b32_e32 v120, v2
	v_mov_b32_e32 v121, v2
	v_mov_b32_e32 v74, v2
	v_mov_b32_e32 v75, v2
	v_mov_b32_e32 v76, v2
	v_mov_b32_e32 v77, v2
	v_mov_b32_e32 v78, v2
	v_mov_b32_e32 v79, v2
	v_mov_b32_e32 v80, v2
	v_mov_b32_e32 v81, v2
	v_mov_b32_e32 v90, v2
	v_mov_b32_e32 v91, v2
	v_mov_b32_e32 v92, v2
	v_mov_b32_e32 v93, v2
	v_mov_b32_e32 v94, v2
	v_mov_b32_e32 v95, v2
	v_mov_b32_e32 v96, v2
	v_mov_b32_e32 v97, v2
	v_mov_b32_e32 v106, v2
	v_mov_b32_e32 v107, v2
	v_mov_b32_e32 v108, v2
	v_mov_b32_e32 v109, v2
	v_mov_b32_e32 v110, v2
	v_mov_b32_e32 v111, v2
	v_mov_b32_e32 v112, v2
	v_mov_b32_e32 v113, v2
	v_mov_b32_e32 v126, v2
	v_mov_b32_e32 v127, v2
	v_mov_b32_e32 v128, v2
	v_mov_b32_e32 v129, v2
	v_mov_b32_e32 v130, v2
	v_mov_b32_e32 v131, v2
	v_mov_b32_e32 v132, v2
	v_mov_b32_e32 v133, v2
	.p2align 6
